# stack11: nt on P6 (eu) pdot stores to keep the u-table slice resident in L2
# speedup vs baseline: 1.0562x; 1.0098x over previous
; DI void eu_load(const unsigned char* __restrict__ ub8, const int id0, const int id1, const int cs, const int lane, uint4 (&u)[16]) {
; #pragma unroll
;   for (int i = 0; i < 16; ++i) {
;     const int id = __shfl(i < 8 ? id0 : id1, (8 * i + (lane >> 3)) & 63, 64);
;     u[i] = *(const uint4*)(ub8 + (size_t)id * 1024 + 128 * cs + 16 * (lane & 7));
;   }
; }
; DI void eu_compute(const uint4 (&u)[16], const uint4& xq, int* __restrict__ pd, const int lane) {
;   int p[16];
; #pragma unroll
;   for (int i = 0; i < 16; ++i) {
;     int acc = __builtin_amdgcn_sdot4((int)u[i].x, (int)xq.x, 0, false);
;     acc = __builtin_amdgcn_sdot4((int)u[i].y, (int)xq.y, acc, false);
;     acc = __builtin_amdgcn_sdot4((int)u[i].z, (int)xq.z, acc, false);
;     p[i] = __builtin_amdgcn_sdot4((int)u[i].w, (int)xq.w, acc, false);
;   }
;   int q8[8], q4[4], q2[2];
;   const bool b2 = lane & 4, b1 = lane & 2, b0 = lane & 1;
; #pragma unroll
;   for (int j = 0; j < 8; ++j) { const int keep = b2 ? p[8 + j] : p[j], send = b2 ? p[j] : p[8 + j]; q8[j] = keep + __shfl_xor(send, 4, 64); }
; #pragma unroll
;   for (int j = 0; j < 4; ++j) { const int keep = b1 ? q8[4 + j] : q8[j], send = b1 ? q8[j] : q8[4 + j]; q4[j] = keep + __shfl_xor(send, 2, 64); }
; #pragma unroll
;   for (int j = 0; j < 2; ++j) { const int keep = b0 ? q4[2 + j] : q4[j], send = b0 ? q4[j] : q4[2 + j]; q2[j] = keep + __shfl_xor(send, 1, 64); }
;   const int slot0 = 16 * (lane & 7) + (lane >> 3);
;   pd[slot0] = q2[0];
;   pd[slot0 + 8] = q2[1];
; }
.LBB0_460:
	s_waitcnt vmcnt(1)
	ds_bpermute_b32 v98, v134, v101
	s_add_i32 s0, s19, -1
	ds_bpermute_b32 v100, v135, v101
	ds_bpermute_b32 v102, v136, v101
	ds_bpermute_b32 v104, v137, v101
	ds_bpermute_b32 v106, v138, v101
	ds_bpermute_b32 v108, v139, v101
	ds_bpermute_b32 v110, v140, v101
	ds_bpermute_b32 v112, v141, v101
	ds_bpermute_b32 v114, v134, v99
	ds_bpermute_b32 v116, v135, v99
	ds_bpermute_b32 v118, v136, v99
	ds_bpermute_b32 v120, v137, v99
	ds_bpermute_b32 v122, v138, v99
	ds_bpermute_b32 v124, v139, v99
	ds_bpermute_b32 v126, v140, v99
	ds_bpermute_b32 v128, v141, v99
	s_min_i32 s22, s0, s29
	v_mov_b32_e32 v163, 0
	s_min_i32 s1, s19, s29
	s_mul_i32 s22, s22, s5
	v_mov_b32_e32 v149, 0
	v_mov_b32_e32 v150, 0
	v_mov_b32_e32 v151, 0
	v_mov_b32_e32 v152, 0
	v_mov_b32_e32 v153, 0
	v_mov_b32_e32 v154, 0
	v_mov_b32_e32 v155, 0
	v_mov_b32_e32 v156, 0
	v_mov_b32_e32 v157, 0
	v_mov_b32_e32 v158, 0
	v_mov_b32_e32 v159, 0
	v_mov_b32_e32 v160, 0
	v_mov_b32_e32 v161, 0
	v_mov_b32_e32 v162, 0
	v_mov_b32_e32 v164, 0
	s_waitcnt vmcnt(0)
	v_dot4c_i32_i8_e32 v163, v6, v46
	s_mul_i32 s1, s1, s5
	s_add_i32 s22, s22, s33
	s_ashr_i32 s27, s26, 31
	v_dot4c_i32_i8_e32 v149, v66, v46
	v_dot4c_i32_i8_e32 v150, v62, v46
	v_dot4c_i32_i8_e32 v151, v58, v46
	v_dot4c_i32_i8_e32 v152, v54, v46
	v_dot4c_i32_i8_e32 v153, v50, v46
	v_dot4c_i32_i8_e32 v154, v42, v46
	v_dot4c_i32_i8_e32 v155, v38, v46
	v_dot4c_i32_i8_e32 v156, v34, v46
	v_dot4c_i32_i8_e32 v157, v30, v46
	v_dot4c_i32_i8_e32 v158, v26, v46
	v_dot4c_i32_i8_e32 v159, v22, v46
	v_dot4c_i32_i8_e32 v160, v18, v46
	v_dot4c_i32_i8_e32 v161, v14, v46
	v_dot4c_i32_i8_e32 v162, v10, v46
	v_dot4c_i32_i8_e32 v164, v70, v46
	v_dot4c_i32_i8_e32 v163, v7, v47
	s_add_i32 s1, s1, s33
	s_lshl_b32 s22, s22, 3
	s_lshl_b64 s[26:27], s[26:27], 9
	v_dot4c_i32_i8_e32 v149, v67, v47
	v_dot4c_i32_i8_e32 v150, v63, v47
	v_dot4c_i32_i8_e32 v151, v59, v47
	v_dot4c_i32_i8_e32 v152, v55, v47
	v_dot4c_i32_i8_e32 v153, v51, v47
	v_dot4c_i32_i8_e32 v154, v43, v47
	v_dot4c_i32_i8_e32 v155, v39, v47
	v_dot4c_i32_i8_e32 v156, v35, v47
	v_dot4c_i32_i8_e32 v157, v31, v47
	v_dot4c_i32_i8_e32 v158, v27, v47
	v_dot4c_i32_i8_e32 v159, v23, v47
	v_dot4c_i32_i8_e32 v160, v19, v47
	v_dot4c_i32_i8_e32 v161, v15, v47
	v_dot4c_i32_i8_e32 v162, v11, v47
	v_dot4c_i32_i8_e32 v164, v71, v47
	v_dot4c_i32_i8_e32 v163, v8, v48
	s_lshl_b32 s1, s1, 3
	s_waitcnt lgkmcnt(14)
	s_add_i32 s30, s22, s3
	s_ashr_i32 s25, s24, 31
	v_lshl_add_u64 v[6:7], v[96:97], 0, s[26:27]
	v_dot4c_i32_i8_e32 v149, v68, v48
	v_dot4c_i32_i8_e32 v150, v64, v48
	v_dot4c_i32_i8_e32 v151, v60, v48
	v_dot4c_i32_i8_e32 v152, v56, v48
	v_dot4c_i32_i8_e32 v153, v52, v48
	v_dot4c_i32_i8_e32 v154, v44, v48
	v_dot4c_i32_i8_e32 v155, v40, v48
	v_dot4c_i32_i8_e32 v156, v36, v48
	v_dot4c_i32_i8_e32 v157, v32, v48
	v_dot4c_i32_i8_e32 v158, v28, v48
	v_dot4c_i32_i8_e32 v159, v24, v48
	v_dot4c_i32_i8_e32 v160, v20, v48
	v_dot4c_i32_i8_e32 v161, v16, v48
	v_dot4c_i32_i8_e32 v162, v12, v48
	v_dot4c_i32_i8_e32 v164, v72, v48
	v_dot4c_i32_i8_e32 v163, v9, v49
	s_add_i32 s26, s1, s3
	s_waitcnt lgkmcnt(13)
	s_waitcnt lgkmcnt(12)
	s_waitcnt lgkmcnt(11)
	s_waitcnt lgkmcnt(10)
	s_waitcnt lgkmcnt(9)
	s_waitcnt lgkmcnt(8)
	s_waitcnt lgkmcnt(7)
	s_waitcnt lgkmcnt(6)
	s_waitcnt lgkmcnt(5)
	s_waitcnt lgkmcnt(4)
	s_waitcnt lgkmcnt(3)
	s_waitcnt lgkmcnt(2)
	s_waitcnt lgkmcnt(1)
	s_waitcnt lgkmcnt(0)
	s_ashr_i32 s31, s30, 31
	s_lshl_b64 s[24:25], s[24:25], 9
	v_dot4c_i32_i8_e32 v149, v69, v49
	v_dot4c_i32_i8_e32 v150, v65, v49
	v_dot4c_i32_i8_e32 v151, v61, v49
	v_dot4c_i32_i8_e32 v152, v57, v49
	v_dot4c_i32_i8_e32 v153, v53, v49
	v_dot4c_i32_i8_e32 v154, v45, v49
	v_dot4c_i32_i8_e32 v155, v41, v49
	v_dot4c_i32_i8_e32 v156, v37, v49
	v_dot4c_i32_i8_e32 v157, v33, v49
	v_dot4c_i32_i8_e32 v158, v29, v49
	v_dot4c_i32_i8_e32 v159, v25, v49
	v_dot4c_i32_i8_e32 v160, v21, v49
	v_dot4c_i32_i8_e32 v161, v17, v49
	v_dot4c_i32_i8_e32 v162, v13, v49
	v_dot4c_i32_i8_e32 v164, v73, v49
	s_ashr_i32 s27, s26, 31
	v_lshl_add_u32 v8, v98, 10, v211
	s_lshl_b64 s[38:39], s[30:31], 9
	v_lshl_add_u64 v[130:131], v[96:97], 0, s[24:25]
	v_cndmask_b32_e64 v44, v157, v149, s[6:7]
	v_cndmask_b32_e64 v40, v149, v157, s[6:7]
	v_cndmask_b32_e64 v45, v158, v150, s[6:7]
	v_cndmask_b32_e64 v41, v150, v158, s[6:7]
	v_cndmask_b32_e64 v50, v159, v151, s[6:7]
	v_cndmask_b32_e64 v42, v151, v159, s[6:7]
	v_cndmask_b32_e64 v51, v160, v152, s[6:7]
	v_cndmask_b32_e64 v43, v152, v160, s[6:7]
	v_cndmask_b32_e64 v52, v161, v153, s[6:7]
	v_cndmask_b32_e64 v46, v153, v161, s[6:7]
	v_cndmask_b32_e64 v53, v162, v154, s[6:7]
	v_cndmask_b32_e64 v47, v154, v162, s[6:7]
	v_cndmask_b32_e64 v54, v163, v155, s[6:7]
	v_cndmask_b32_e64 v48, v155, v163, s[6:7]
	v_cndmask_b32_e64 v55, v164, v156, s[6:7]
	v_cndmask_b32_e64 v49, v156, v164, s[6:7]
	s_mov_b32 s24, s26
	s_lshl_b64 s[34:35], s[26:27], 9
	s_lshl_b64 s[36:37], s[26:27], 10
	s_mov_b32 s26, s30
	v_lshl_add_u32 v10, v100, 10, v211
	v_lshl_add_u32 v12, v102, 10, v211
	v_lshl_add_u32 v14, v104, 10, v211
	v_lshl_add_u32 v16, v106, 10, v211
	v_lshl_add_u32 v18, v108, 10, v211
	v_lshl_add_u32 v20, v110, 10, v211
	v_lshl_add_u32 v22, v112, 10, v211
	v_lshl_add_u32 v24, v114, 10, v211
	v_lshl_add_u32 v26, v116, 10, v211
	v_lshl_add_u32 v28, v118, 10, v211
	v_lshl_add_u32 v30, v120, 10, v211
	v_lshl_add_u32 v32, v122, 10, v211
	v_lshl_add_u32 v34, v124, 10, v211
	v_lshl_add_u32 v36, v126, 10, v211
	v_lshl_add_u32 v38, v128, 10, v211
	s_lshl_b64 s[30:31], s[30:31], 10
	global_load_dwordx4 v[102:105], v8, s[100:101]
	global_load_dwordx4 v[106:109], v10, s[100:101]
	global_load_dwordx4 v[110:113], v12, s[100:101]
	global_load_dwordx4 v[114:117], v14, s[100:101]
	global_load_dwordx4 v[118:121], v16, s[100:101]
	global_load_dwordx4 v[122:125], v18, s[100:101]
	global_load_dwordx4 v[126:129], v20, s[100:101]
	global_load_dwordx4 v[150:153], v22, s[100:101]
	global_load_dwordx4 v[154:157], v24, s[100:101]
	global_load_dwordx4 v[158:161], v26, s[100:101]
	global_load_dwordx4 v[174:177], v28, s[100:101]
	global_load_dwordx4 v[178:181], v30, s[100:101]
	global_load_dwordx4 v[182:185], v32, s[100:101]
	global_load_dwordx4 v[186:189], v34, s[100:101]
	global_load_dwordx4 v[190:193], v36, s[100:101]
	global_load_dwordx4 v[194:197], v38, s[100:101]
	v_lshl_add_u64 v[8:9], v[76:77], 0, s[38:39]
	ds_bpermute_b32 v60, v146, v46
	ds_bpermute_b32 v61, v146, v47
	ds_bpermute_b32 v62, v146, v48
	ds_bpermute_b32 v63, v146, v49
	v_lshl_add_u64 v[10:11], v[94:95], 0, s[30:31]
	global_load_dword v13, v[8:9], off
	s_nop 0
	global_load_dword v9, v[8:9], off offset:256
	s_nop 0
	global_load_dwordx4 v[46:49], v[10:11], off
	ds_bpermute_b32 v56, v146, v40
	ds_bpermute_b32 v57, v146, v41
	ds_bpermute_b32 v58, v146, v42
	ds_bpermute_b32 v59, v146, v43
	s_waitcnt lgkmcnt(7)
; #define EU_IDS(t, i0, i1, xq) do { i0 = sel_i[(size_t)(t) * 128 + lane]; i1 = sel_i[(size_t)(t) * 128 + 64 + lane]; \
;                                    xq = *(const uint4*)(h1f8 + (size_t)(t) * 1024 + 128 * cs + 16 * (lane & 7)); } while (0)
; DI void eu_compute(const uint4 (&u)[16], const uint4& xq, int* __restrict__ pd, const int lane) {
;     ...
;   for (int j = 0; j < 8; ++j) { const int keep = b2 ? p[8 + j] : p[j], send = b2 ? p[j] : p[8 + j]; q8[j] = keep + __shfl_xor(send, 4, 64); }
; #pragma unroll
;   for (int j = 0; j < 4; ++j) { const int keep = b1 ? q8[4 + j] : q8[j], send = b1 ? q8[j] : q8[4 + j]; q4[j] = keep + __shfl_xor(send, 2, 64); }
; #pragma unroll
;   for (int j = 0; j < 2; ++j) { const int keep = b0 ? q4[2 + j] : q4[j], send = b0 ? q4[j] : q4[2 + j]; q2[j] = keep + __shfl_xor(send, 1, 64); }
;   const int slot0 = 16 * (lane & 7) + (lane >> 3);
;   pd[slot0] = q2[0];
;   pd[slot0 + 8] = q2[1];
; }
; DI void phase_eu(const Params& p, const unsigned my_xcc, const unsigned my_rank) {
;     ...
;     for (int k = 0; k < K; k += 2) {
;       eu_load(ub8, b0, b1, cs, lane, uB);
;       const int tA2 = TOK(k + 2); int na0, na1; uint4 nxa;
;       EU_IDS(tA2, na0, na1, nxa);
;       eu_compute(uA, xa, pd + (size_t)tA * 128, lane);
;       eu_load(ub8, na0, na1, cs, lane, uA);
;       const int tB2 = TOK(k + 3); int nb0, nb1; uint4 nxb;
;       EU_IDS(tB2, nb0, nb1, nxb);
;       eu_compute(uB, xb, pd + (size_t)tB * 128, lane);
	v_add_u32_e32 v14, v60, v52
	s_waitcnt lgkmcnt(3)
	v_add_u32_e32 v8, v56, v44
	s_waitcnt lgkmcnt(2)
	v_add_u32_e32 v10, v57, v45
	s_waitcnt lgkmcnt(1)
	v_add_u32_e32 v11, v58, v50
	s_waitcnt lgkmcnt(0)
	v_add_u32_e32 v12, v59, v51
	v_add_u32_e32 v15, v61, v53
	v_add_u32_e32 v16, v62, v54
	v_add_u32_e32 v17, v63, v55
	v_cndmask_b32_e64 v18, v14, v8, s[8:9]
	v_cndmask_b32_e64 v8, v8, v14, s[8:9]
	v_cndmask_b32_e64 v14, v15, v10, s[8:9]
	v_cndmask_b32_e64 v10, v10, v15, s[8:9]
	v_cndmask_b32_e64 v15, v16, v11, s[8:9]
	v_cndmask_b32_e64 v11, v11, v16, s[8:9]
	v_cndmask_b32_e64 v16, v17, v12, s[8:9]
	v_cndmask_b32_e64 v12, v12, v17, s[8:9]
	ds_bpermute_b32 v8, v147, v8
	ds_bpermute_b32 v10, v147, v10
	ds_bpermute_b32 v11, v147, v11
	ds_bpermute_b32 v12, v147, v12
	v_mov_b32_e32 v165, 0
	s_waitcnt lgkmcnt(3)
	v_add_u32_e32 v8, v8, v18
	s_waitcnt lgkmcnt(2)
	v_add_u32_e32 v10, v10, v14
	s_waitcnt lgkmcnt(1)
	v_add_u32_e32 v11, v11, v15
	s_waitcnt lgkmcnt(0)
	v_add_u32_e32 v12, v12, v16
	v_cndmask_b32_e64 v14, v11, v8, s[10:11]
	v_cndmask_b32_e64 v8, v8, v11, s[10:11]
	v_cndmask_b32_e64 v11, v12, v10, s[10:11]
	v_cndmask_b32_e64 v10, v10, v12, s[10:11]
	ds_bpermute_b32 v8, v148, v8
	ds_bpermute_b32 v10, v148, v10
	v_mov_b32_e32 v166, 0
	v_mov_b32_e32 v167, 0
	v_mov_b32_e32 v168, 0
	v_mov_b32_e32 v169, 0
	v_mov_b32_e32 v170, 0
	v_mov_b32_e32 v171, 0
	v_mov_b32_e32 v172, 0
	v_mov_b32_e32 v173, 0
	v_mov_b32_e32 v198, 0
	v_mov_b32_e32 v199, 0
	v_mov_b32_e32 v206, 0
	v_mov_b32_e32 v207, 0
	v_mov_b32_e32 v208, 0
	v_mov_b32_e32 v209, 0
	v_mov_b32_e32 v210, 0
	s_waitcnt lgkmcnt(1)
	v_add_u32_e32 v8, v8, v14
	s_waitcnt lgkmcnt(0)
	v_add_u32_e32 v10, v10, v11
	global_store_dword v[6:7], v8, off nt
	global_store_dword v[6:7], v10, off offset:32 nt
	v_lshl_add_u64 v[40:41], v[76:77], 0, s[34:35]
	v_lshl_add_u64 v[42:43], v[94:95], 0, s[36:37]
	global_load_dword v101, v[40:41], off
	global_load_dword v99, v[40:41], off offset:256
	global_load_dwordx4 v[202:205], v[42:43], off
	s_add_i32 s19, s19, 2
	s_waitcnt vmcnt(23)
	v_dot4c_i32_i8_e32 v165, v102, v2
	s_waitcnt vmcnt(22)
	v_dot4c_i32_i8_e32 v166, v106, v2
	s_waitcnt vmcnt(21)
	v_dot4c_i32_i8_e32 v167, v110, v2
	s_waitcnt vmcnt(20)
	v_dot4c_i32_i8_e32 v168, v114, v2
	s_waitcnt vmcnt(19)
	v_dot4c_i32_i8_e32 v169, v118, v2
	s_waitcnt vmcnt(18)
	v_dot4c_i32_i8_e32 v170, v122, v2
	s_waitcnt vmcnt(17)
	v_dot4c_i32_i8_e32 v171, v126, v2
	s_waitcnt vmcnt(16)
	v_dot4c_i32_i8_e32 v172, v150, v2
	s_waitcnt vmcnt(15)
	v_dot4c_i32_i8_e32 v173, v154, v2
	s_waitcnt vmcnt(14)
	v_dot4c_i32_i8_e32 v198, v158, v2
	s_waitcnt vmcnt(13)
	v_dot4c_i32_i8_e32 v199, v174, v2
	s_waitcnt vmcnt(12)
	v_dot4c_i32_i8_e32 v206, v178, v2
	s_waitcnt vmcnt(11)
	v_dot4c_i32_i8_e32 v207, v182, v2
	s_waitcnt vmcnt(10)
	v_dot4c_i32_i8_e32 v208, v186, v2
	s_waitcnt vmcnt(9)
	v_dot4c_i32_i8_e32 v209, v190, v2
	s_waitcnt vmcnt(8)
	v_dot4c_i32_i8_e32 v210, v194, v2
	v_dot4c_i32_i8_e32 v165, v103, v3
	v_dot4c_i32_i8_e32 v166, v107, v3
	v_dot4c_i32_i8_e32 v167, v111, v3
	v_dot4c_i32_i8_e32 v168, v115, v3
	s_waitcnt vmcnt(7)
	ds_bpermute_b32 v2, v134, v13
	ds_bpermute_b32 v6, v135, v13
	ds_bpermute_b32 v8, v136, v13
	ds_bpermute_b32 v10, v137, v13
	ds_bpermute_b32 v12, v138, v13
	ds_bpermute_b32 v14, v139, v13
	ds_bpermute_b32 v16, v140, v13
	ds_bpermute_b32 v18, v141, v13
	s_waitcnt vmcnt(6)
	ds_bpermute_b32 v20, v134, v9
	ds_bpermute_b32 v22, v135, v9
	ds_bpermute_b32 v24, v136, v9
	ds_bpermute_b32 v26, v137, v9
	ds_bpermute_b32 v28, v138, v9
	ds_bpermute_b32 v30, v139, v9
	ds_bpermute_b32 v32, v140, v9
	ds_bpermute_b32 v34, v141, v9
	v_dot4c_i32_i8_e32 v169, v119, v3
	v_dot4c_i32_i8_e32 v170, v123, v3
	v_dot4c_i32_i8_e32 v171, v127, v3
	v_dot4c_i32_i8_e32 v172, v151, v3
	v_dot4c_i32_i8_e32 v173, v155, v3
	v_dot4c_i32_i8_e32 v198, v159, v3
	v_dot4c_i32_i8_e32 v199, v175, v3
	v_dot4c_i32_i8_e32 v206, v179, v3
	v_dot4c_i32_i8_e32 v207, v183, v3
	v_dot4c_i32_i8_e32 v208, v187, v3
	v_dot4c_i32_i8_e32 v209, v191, v3
	v_dot4c_i32_i8_e32 v210, v195, v3
	s_waitcnt lgkmcnt(14)
	s_waitcnt lgkmcnt(13)
	s_waitcnt lgkmcnt(12)
	s_waitcnt lgkmcnt(11)
	s_waitcnt lgkmcnt(10)
	s_waitcnt lgkmcnt(9)
	s_waitcnt lgkmcnt(8)
	s_waitcnt lgkmcnt(7)
	s_waitcnt lgkmcnt(6)
	s_waitcnt lgkmcnt(5)
	s_waitcnt lgkmcnt(4)
	s_waitcnt lgkmcnt(3)
	s_waitcnt lgkmcnt(2)
	s_waitcnt lgkmcnt(1)
	s_waitcnt lgkmcnt(0)
; DI void eu_load(const unsigned char* __restrict__ ub8, const int id0, const int id1, const int cs, const int lane, uint4 (&u)[16]) {
; #pragma unroll
;   for (int i = 0; i < 16; ++i) {
;     const int id = __shfl(i < 8 ? id0 : id1, (8 * i + (lane >> 3)) & 63, 64);
;     u[i] = *(const uint4*)(ub8 + (size_t)id * 1024 + 128 * cs + 16 * (lane & 7));
;   }
; }
; DI void eu_compute(const uint4 (&u)[16], const uint4& xq, int* __restrict__ pd, const int lane) {
;   int p[16];
; #pragma unroll
;   for (int i = 0; i < 16; ++i) {
;     int acc = __builtin_amdgcn_sdot4((int)u[i].x, (int)xq.x, 0, false);
;     acc = __builtin_amdgcn_sdot4((int)u[i].y, (int)xq.y, acc, false);
;     acc = __builtin_amdgcn_sdot4((int)u[i].z, (int)xq.z, acc, false);
;     p[i] = __builtin_amdgcn_sdot4((int)u[i].w, (int)xq.w, acc, false);
;   }
;   int q8[8], q4[4], q2[2];
;   const bool b2 = lane & 4, b1 = lane & 2, b0 = lane & 1;
; #pragma unroll
;   for (int j = 0; j < 8; ++j) { const int keep = b2 ? p[8 + j] : p[j], send = b2 ? p[j] : p[8 + j]; q8[j] = keep + __shfl_xor(send, 4, 64); }
; #pragma unroll
;   for (int j = 0; j < 4; ++j) { const int keep = b1 ? q8[4 + j] : q8[j], send = b1 ? q8[j] : q8[4 + j]; q4[j] = keep + __shfl_xor(send, 2, 64); }
; #pragma unroll
;   for (int j = 0; j < 2; ++j) { const int keep = b0 ? q4[2 + j] : q4[j], send = b0 ? q4[j] : q4[2 + j]; q2[j] = keep + __shfl_xor(send, 1, 64); }
;   const int slot0 = 16 * (lane & 7) + (lane >> 3);
;   pd[slot0] = q2[0];
;   pd[slot0 + 8] = q2[1];
; }
	v_lshl_add_u32 v2, v2, 10, v211
	v_lshl_add_u32 v6, v6, 10, v211
	v_lshl_add_u32 v8, v8, 10, v211
	v_lshl_add_u32 v10, v10, 10, v211
	v_lshl_add_u32 v12, v12, 10, v211
	v_lshl_add_u32 v14, v14, 10, v211
	v_lshl_add_u32 v16, v16, 10, v211
	v_lshl_add_u32 v18, v18, 10, v211
	v_lshl_add_u32 v20, v20, 10, v211
	v_lshl_add_u32 v22, v22, 10, v211
	v_lshl_add_u32 v24, v24, 10, v211
	v_lshl_add_u32 v70, v26, 10, v211
	v_lshl_add_u32 v72, v28, 10, v211
	v_lshl_add_u32 v102, v30, 10, v211
	v_lshl_add_u32 v106, v32, 10, v211
	v_lshl_add_u32 v110, v34, 10, v211
	global_load_dwordx4 v[66:69], v2, s[100:101]
	global_load_dwordx4 v[62:65], v6, s[100:101]
	global_load_dwordx4 v[58:61], v8, s[100:101]
	global_load_dwordx4 v[54:57], v10, s[100:101]
	global_load_dwordx4 v[50:53], v12, s[100:101]
	global_load_dwordx4 v[42:45], v14, s[100:101]
	global_load_dwordx4 v[38:41], v16, s[100:101]
	global_load_dwordx4 v[34:37], v18, s[100:101]
	global_load_dwordx4 v[30:33], v20, s[100:101]
	global_load_dwordx4 v[26:29], v22, s[100:101]
	s_nop 0
	global_load_dwordx4 v[22:25], v24, s[100:101]
	s_nop 0
	global_load_dwordx4 v[18:21], v70, s[100:101]
	global_load_dwordx4 v[14:17], v72, s[100:101]
	global_load_dwordx4 v[10:13], v102, s[100:101]
	global_load_dwordx4 v[6:9], v106, s[100:101]
	s_nop 0
	global_load_dwordx4 v[70:73], v110, s[100:101]
	v_dot4c_i32_i8_e32 v165, v104, v4
	v_dot4c_i32_i8_e32 v166, v108, v4
	v_dot4c_i32_i8_e32 v167, v112, v4
	v_dot4c_i32_i8_e32 v168, v116, v4
	v_dot4c_i32_i8_e32 v169, v120, v4
	v_dot4c_i32_i8_e32 v170, v124, v4
	v_dot4c_i32_i8_e32 v171, v128, v4
	v_dot4c_i32_i8_e32 v173, v156, v4
	v_dot4c_i32_i8_e32 v198, v160, v4
	v_dot4c_i32_i8_e32 v199, v176, v4
	v_dot4c_i32_i8_e32 v206, v180, v4
	v_dot4c_i32_i8_e32 v207, v184, v4
	v_dot4c_i32_i8_e32 v208, v188, v4
	v_dot4c_i32_i8_e32 v209, v192, v4
	v_dot4c_i32_i8_e32 v172, v152, v4
	v_dot4c_i32_i8_e32 v210, v196, v4
	v_dot4c_i32_i8_e32 v165, v105, v5
	v_dot4c_i32_i8_e32 v166, v109, v5
	v_dot4c_i32_i8_e32 v167, v113, v5
	v_dot4c_i32_i8_e32 v168, v117, v5
	v_dot4c_i32_i8_e32 v169, v121, v5
	v_dot4c_i32_i8_e32 v170, v125, v5
	v_dot4c_i32_i8_e32 v171, v129, v5
	v_dot4c_i32_i8_e32 v173, v157, v5
	v_dot4c_i32_i8_e32 v198, v161, v5
	v_dot4c_i32_i8_e32 v199, v177, v5
	v_dot4c_i32_i8_e32 v206, v181, v5
	v_dot4c_i32_i8_e32 v207, v185, v5
	v_dot4c_i32_i8_e32 v208, v189, v5
	v_dot4c_i32_i8_e32 v209, v193, v5
	v_dot4c_i32_i8_e32 v172, v153, v5
	v_dot4c_i32_i8_e32 v210, v197, v5
	v_cndmask_b32_e64 v3, v165, v173, s[6:7]
	v_cndmask_b32_e64 v5, v166, v198, s[6:7]
	v_cndmask_b32_e64 v100, v167, v199, s[6:7]
	v_cndmask_b32_e64 v103, v168, v206, s[6:7]
	v_cndmask_b32_e64 v105, v169, v207, s[6:7]
	v_cndmask_b32_e64 v107, v170, v208, s[6:7]
	v_cndmask_b32_e64 v109, v171, v209, s[6:7]
	v_cndmask_b32_e64 v111, v172, v210, s[6:7]
	ds_bpermute_b32 v3, v146, v3
	ds_bpermute_b32 v5, v146, v5
	ds_bpermute_b32 v100, v146, v100
	ds_bpermute_b32 v103, v146, v103
	ds_bpermute_b32 v105, v146, v105
	ds_bpermute_b32 v107, v146, v107
	ds_bpermute_b32 v109, v146, v109
	ds_bpermute_b32 v111, v146, v111
	v_cndmask_b32_e64 v2, v173, v165, s[6:7]
	v_cndmask_b32_e64 v4, v198, v166, s[6:7]
	v_cndmask_b32_e64 v98, v199, v167, s[6:7]
	v_cndmask_b32_e64 v102, v206, v168, s[6:7]
	v_cndmask_b32_e64 v104, v207, v169, s[6:7]
	v_cndmask_b32_e64 v106, v208, v170, s[6:7]
	v_cndmask_b32_e64 v108, v209, v171, s[6:7]
	v_cndmask_b32_e64 v110, v210, v172, s[6:7]
	s_waitcnt lgkmcnt(7)
	v_add_u32_e32 v2, v3, v2
	s_waitcnt lgkmcnt(6)
	v_add_u32_e32 v3, v5, v4
	s_waitcnt lgkmcnt(5)
	v_add_u32_e32 v4, v100, v98
	s_waitcnt lgkmcnt(4)
	v_add_u32_e32 v5, v103, v102
	s_waitcnt lgkmcnt(3)
	v_add_u32_e32 v98, v105, v104
	s_waitcnt lgkmcnt(2)
	v_add_u32_e32 v100, v107, v106
	s_waitcnt lgkmcnt(1)
	v_add_u32_e32 v102, v109, v108
	s_waitcnt lgkmcnt(0)
	v_add_u32_e32 v103, v111, v110
	v_cndmask_b32_e64 v104, v98, v2, s[8:9]
	v_cndmask_b32_e64 v2, v2, v98, s[8:9]
	v_cndmask_b32_e64 v98, v100, v3, s[8:9]
	v_cndmask_b32_e64 v3, v3, v100, s[8:9]
	v_cndmask_b32_e64 v100, v102, v4, s[8:9]
	v_cndmask_b32_e64 v4, v4, v102, s[8:9]
	v_cndmask_b32_e64 v102, v103, v5, s[8:9]
	v_cndmask_b32_e64 v5, v5, v103, s[8:9]
	ds_bpermute_b32 v2, v147, v2
	ds_bpermute_b32 v4, v147, v4
	ds_bpermute_b32 v3, v147, v3
	ds_bpermute_b32 v5, v147, v5
	s_cmp_lt_i32 s0, s28
	s_waitcnt lgkmcnt(3)
	v_add_u32_e32 v2, v2, v104
	s_waitcnt lgkmcnt(2)
	v_add_u32_e32 v4, v4, v100
	s_waitcnt lgkmcnt(1)
	v_add_u32_e32 v3, v3, v98
	s_waitcnt lgkmcnt(0)
	v_add_u32_e32 v5, v5, v102
	v_cndmask_b32_e64 v98, v4, v2, s[10:11]
	v_cndmask_b32_e64 v2, v2, v4, s[10:11]
	v_cndmask_b32_e64 v4, v3, v5, s[10:11]
	ds_bpermute_b32 v100, v148, v2
	ds_bpermute_b32 v102, v148, v4
	v_cndmask_b32_e64 v103, v5, v3, s[10:11]
	s_waitcnt vmcnt(16)
	v_mov_b64_e32 v[2:3], v[202:203]
	v_mov_b64_e32 v[4:5], v[204:205]
	s_waitcnt lgkmcnt(1)
	v_add_u32_e32 v98, v100, v98
	s_waitcnt lgkmcnt(0)
	v_add_u32_e32 v100, v102, v103
	global_store_dword v[130:131], v98, off nt
	global_store_dword v[130:131], v100, off offset:32 nt
	s_cbranch_scc1 .LBB0_460
	s_branch .LBB0_455
